# GEMM K-loops without per-segment s_setprio flips plus one static s_setprio 1 for the trailing wave half (waves 4-7) for the whole GEMM phase
# speedup vs baseline: 1.0027x; 1.0027x over previous
; #define PG8_STAGE(bufoff, gbase, voff) do { _Pragma("unroll") for (int _i = 0; _i < 2; ++_i) \
;         __builtin_amdgcn_global_load_lds((const unsigned*)((const char*)(gbase) + (voff)[_i]), (PG8_LAS unsigned*)(lds + (bufoff) + ldsw + _i * 8192), 16, 0, 0); } while (0)
; #define PG8_BAR __builtin_amdgcn_s_barrier()
; template <class Epi, class Sched, bool ALIGN_EPI = false, bool SP2 = false>
; __device__ __forceinline__ void gemm_phase(PG8_LAS unsigned char* lds, const Gemm g, const Sched& S, const Epi& E) {
;     ...
;     for (int i = 0; i < 2; ++i) { int R, C; stage_rc(tid * 16 + i * 8192, R, C); const int Rb = Epi::PERM ? (64 * (R >> 5) + perm32(R & 31)) : R;
;         voffA[i] = (unsigned)(R * K + C) * 2u; voffB[i] = (unsigned)(Rb * K + C) * 2u; }
;     ...
;         PG8_STAGE(PG8_SB(0, 0), cB, voffB); PG8_STAGE(PG8_SB(0, 1), cB + hstepB, voffB); PG8_STAGE(PG8_SA(0, 0), cA, voffA); PG8_STAGE(PG8_SA(0, 1), cA + hstep, voffA);
;         if (wr == 1) PG8_BAR;
.LBB0_163:
	s_or_b64 exec, exec, s[26:27]
	s_waitcnt vmcnt(0)
	v_bfe_i32 v3, v26, 27, 1
	v_lshlrev_b32_e32 v1, 4, v26
	v_lshrrev_b32_e32 v3, 22, v3
	v_ashrrev_i32_e32 v2, 31, v26
	v_add_u32_e32 v3, v1, v3
	v_lshrrev_b32_e32 v2, 26, v2
	v_and_b32_e32 v3, 0xfffffc00, v3
	v_add_u32_e32 v2, v26, v2
	v_sub_u32_e32 v3, v1, v3
	v_ashrrev_i32_e32 v2, 6, v2
	v_lshrrev_b32_e32 v4, 4, v3
	v_bitop3_b32 v4, v4, v3, 32 bitop3:0x6c
	v_lshlrev_b32_e32 v3, 3, v2
	v_and_b32_e32 v5, -16, v3
	v_ashrrev_i32_e32 v3, 31, v4
	v_lshrrev_b32_e32 v3, 26, v3
	v_add_u32_e32 v6, v4, v3
	v_ashrrev_i32_e32 v3, 6, v6
	v_and_b32_e32 v6, 0xc0, v6
	v_sub_u32_e32 v4, v4, v6
	v_lshlrev_b32_e32 v7, 5, v2
	v_ashrrev_i16_sdwa v4, v225, sext(v4) dst_sel:DWORD dst_unused:UNUSED_PAD src0_sel:DWORD src1_sel:BYTE_0
	v_and_b32_e32 v7, 32, v7
	v_bfe_i32 v4, v4, 0, 16
	v_add_u32_e32 v5, v3, v5
	v_add_lshl_u32 v7, v7, v4, 1
	v_add_u32_e32 v1, 0x2000, v1
	v_lshlrev_b32_e32 v6, 1, v5
	v_lshrrev_b32_e32 v8, 2, v5
	v_lshl_add_u32 v130, v5, 12, v7
	v_ashrrev_i32_e32 v5, 31, v1
	v_lshrrev_b32_e32 v5, 22, v5
	v_and_b32_e32 v8, 4, v8
	v_and_b32_e32 v9, 3, v3
	v_and_b32_e32 v6, 0xfffd8, v6
	v_add_u32_e32 v5, v1, v5
	v_or3_b32 v6, v9, v8, v6
	v_ashrrev_i32_e32 v5, 10, v5
	v_lshl_add_u32 v132, v6, 12, v7
	v_mul_i32_i24_e32 v6, 0x400, v5
	v_sub_u32_e32 v1, v1, v6
	v_lshrrev_b32_e32 v6, 4, v1
	v_bitop3_b32 v1, v6, v1, 32 bitop3:0x6c
	v_lshlrev_b32_e32 v6, 3, v5
	v_and_b32_e32 v7, -16, v6
	v_ashrrev_i32_e32 v6, 31, v1
	v_lshrrev_b32_e32 v6, 26, v6
	v_add_u32_e32 v8, v1, v6
	v_ashrrev_i32_e32 v6, 6, v8
	v_add_u32_e32 v9, v6, v7
	v_lshlrev_b32_e32 v7, 5, v5
	v_and_b32_e32 v10, 32, v7
	v_and_b32_e32 v7, 0xc0, v8
	v_sub_u32_e32 v1, v1, v7
	s_ashr_i32 s4, s36, 6
	v_ashrrev_i16_sdwa v1, v225, sext(v1) dst_sel:DWORD dst_unused:UNUSED_PAD src0_sel:DWORD src1_sel:BYTE_0
	v_bfe_i32 v7, v1, 0, 16
	v_lshlrev_b32_e32 v1, 1, v9
	v_lshrrev_b32_e32 v8, 2, v9
	s_lshl_b32 s0, s4, 10
	v_and_b32_e32 v8, 4, v8
	v_and_b32_e32 v11, 3, v6
	v_and_b32_e32 v1, 0xfffd8, v1
	s_add_i32 s1, s0, 0
	v_readlane_b32 s6, v254, 24
	v_or3_b32 v1, v11, v8, v1
	v_add_lshl_u32 v8, v10, v7, 1
	s_add_i32 m0, s1, 0x10000
	v_readlane_b32 s7, v254, 25
	v_lshl_add_u32 v136, v1, 12, v8
	s_add_i32 s25, s1, 0x2000
	v_lshl_add_u32 v134, v9, 12, v8
	s_add_i32 s42, s1, 0x4000
	s_add_i32 s51, s1, 0x6000
	global_load_lds_dwordx4 v132, s[6:7]
	s_add_i32 m0, s1, 0x12000
	s_ashr_i32 s5, s36, 8
	global_load_lds_dwordx4 v136, s[6:7]
	v_readlane_b32 s6, v254, 18
	s_add_i32 m0, s1, 0x14000
	v_readlane_b32 s7, v254, 19
	s_nop 4
	global_load_lds_dwordx4 v132, s[6:7]
	s_add_i32 m0, s1, 0x16000
	s_cmp_eq_u32 s5, 1
	global_load_lds_dwordx4 v136, s[6:7]
	v_readlane_b32 s6, v254, 20
	s_mov_b32 m0, s1
	v_readlane_b32 s7, v254, 21
	s_cselect_b64 s[26:27], -1, 0
	s_cmp_lg_u32 s5, 1
	s_nop 2
	global_load_lds_dwordx4 v130, s[6:7]
	s_mov_b32 m0, s25
	s_nop 0
	global_load_lds_dwordx4 v134, s[6:7]
	v_readlane_b32 s6, v254, 22
	s_mov_b32 m0, s42
	v_readlane_b32 s7, v254, 23
	s_nop 4
	global_load_lds_dwordx4 v130, s[6:7]
	s_mov_b32 m0, s51
	s_nop 0
	global_load_lds_dwordx4 v134, s[6:7]
	s_cbranch_scc1 .LBB0_165
	s_barrier
	s_setprio 1

; #define PG8_WAIT_V(n) asm volatile("s_waitcnt vmcnt(" #n ")" ::: "memory")
; #define PG8_BAR __builtin_amdgcn_s_barrier()
; template <class Epi, class Sched, bool ALIGN_EPI = false, bool SP2 = false>
; __device__ __forceinline__ void gemm_phase(PG8_LAS unsigned char* lds, const Gemm g, const Sched& S, const Epi& E) {
;     ...
;     PG8_WAIT_V(0);
;     if constexpr (!ALIGN_EPI) { if (wr == 0) PG8_BAR; }
;     PG8_BAR;
.LBB0_209:
	s_setprio 0
	s_waitcnt vmcnt(0)
	v_readlane_b32 s86, v249, 56
	v_readlane_b32 s87, v249, 57
	s_barrier

; #define PG8_STAGE(bufoff, gbase, voff) do { _Pragma("unroll") for (int _i = 0; _i < 2; ++_i) \
;         __builtin_amdgcn_global_load_lds((const unsigned*)((const char*)(gbase) + (voff)[_i]), (PG8_LAS unsigned*)(lds + (bufoff) + ldsw + _i * 8192), 16, 0, 0); } while (0)
; #define PG8_BAR __builtin_amdgcn_s_barrier()
; template <class Epi, class Sched, bool ALIGN_EPI = false, bool SP2 = false>
; __device__ __forceinline__ void gemm_phase(PG8_LAS unsigned char* lds, const Gemm g, const Sched& S, const Epi& E) {
;     ...
;     for (int i = 0; i < 2; ++i) { int R, C; stage_rc(tid * 16 + i * 8192, R, C); const int Rb = Epi::PERM ? (64 * (R >> 5) + perm32(R & 31)) : R;
;         voffA[i] = (unsigned)(R * K + C) * 2u; voffB[i] = (unsigned)(Rb * K + C) * 2u; }
;     ...
;         PG8_STAGE(PG8_SB(0, 0), cB, voffB); PG8_STAGE(PG8_SB(0, 1), cB + hstepB, voffB); PG8_STAGE(PG8_SA(0, 0), cA, voffA); PG8_STAGE(PG8_SA(0, 1), cA + hstep, voffA);
;         if (wr == 1) PG8_BAR;
.LBB0_778:
	s_andn2_b64 vcc, exec, s[26:27]
	s_cbranch_vccnz .LBB0_849
	v_readlane_b32 s0, v252, 55
	s_waitcnt vmcnt(0) lgkmcnt(0)
	v_mov_b32_e32 v3, v0
	v_readlane_b32 s1, v252, 56
	s_waitcnt lgkmcnt(0)
	s_barrier
	s_andn2_b64 vcc, exec, s[0:1]
	v_readfirstlane_b32 s0, v3
	s_cbranch_vccnz .LBB0_795
	v_lshlrev_b32_e32 v1, 4, v3
	v_add_u32_e32 v4, 0x2000, v1
	v_ashrrev_i32_e32 v2, 31, v4
	v_lshrrev_b32_e32 v2, 22, v2
	v_add_u32_e32 v2, v4, v2
	v_ashrrev_i32_e32 v2, 10, v2
	v_mul_i32_i24_e32 v5, 0x400, v2
	v_sub_u32_e32 v4, v4, v5
	v_lshrrev_b32_e32 v5, 4, v4
	v_bitop3_b32 v5, v5, v4, 32 bitop3:0x6c
	v_ashrrev_i32_e32 v4, 31, v5
	v_lshrrev_b32_e32 v4, 26, v4
	v_add_u32_e32 v6, v5, v4
	v_lshlrev_b32_e32 v8, 3, v2
	v_ashrrev_i32_e32 v4, 6, v6
	v_and_b32_e32 v8, -16, v8
	v_add_u32_e32 v8, v4, v8
	v_lshrrev_b32_e32 v9, 2, v8
	v_lshlrev_b32_e32 v10, 1, v8
	v_and_b32_e32 v6, 0xc0, v6
	v_and_b32_e32 v7, 3, v4
	v_and_b32_e32 v9, 4, v9
	v_and_b32_e32 v10, 0x3fffd8, v10
	v_sub_u32_e32 v5, v5, v6
	v_or3_b32 v7, v7, v9, v10
	v_lshlrev_b32_e32 v9, 5, v2
	v_ashrrev_i16_sdwa v5, v225, sext(v5) dst_sel:DWORD dst_unused:UNUSED_PAD src0_sel:DWORD src1_sel:BYTE_0
	v_and_b32_e32 v9, 32, v9
	v_bfe_i32 v5, v5, 0, 16
	v_add_lshl_u32 v6, v9, v5, 1
	v_lshl_add_u32 v174, v7, 10, v6
	v_lshl_add_u32 v176, v8, 10, v6
	v_bfe_i32 v6, v3, 27, 1
	v_lshrrev_b32_e32 v6, 22, v6
	v_add_u32_e32 v6, v1, v6
	v_and_b32_e32 v6, 0xfffffc00, v6
	v_sub_u32_e32 v1, v1, v6
	v_lshrrev_b32_e32 v6, 4, v1
	v_ashrrev_i32_e32 v7, 31, v3
	v_bitop3_b32 v1, v6, v1, 32 bitop3:0x6c
	v_lshrrev_b32_e32 v7, 26, v7
	v_ashrrev_i32_e32 v6, 31, v1
	v_add_u32_e32 v7, v3, v7
	v_lshrrev_b32_e32 v6, 26, v6
	v_ashrrev_i32_e32 v7, 6, v7
	v_add_u32_e32 v8, v1, v6
	v_lshlrev_b32_e32 v10, 3, v7
	v_ashrrev_i32_e32 v6, 6, v8
	v_and_b32_e32 v10, -16, v10
	v_add_u32_e32 v10, v6, v10
	v_lshrrev_b32_e32 v11, 2, v10
	v_lshlrev_b32_e32 v12, 1, v10
	v_and_b32_e32 v8, 0xc0, v8
	v_and_b32_e32 v9, 3, v6
	v_and_b32_e32 v11, 4, v11
	v_and_b32_e32 v12, 0x3fffd8, v12
	v_sub_u32_e32 v1, v1, v8
	s_ashr_i32 s1, s0, 6
	v_or3_b32 v9, v9, v11, v12
	v_lshlrev_b32_e32 v11, 5, v7
	v_ashrrev_i16_sdwa v1, v225, sext(v1) dst_sel:DWORD dst_unused:UNUSED_PAD src0_sel:DWORD src1_sel:BYTE_0
	s_lshl_b32 s25, s1, 10
	v_and_b32_e32 v11, 32, v11
	v_bfe_i32 v8, v1, 0, 16
	v_add_lshl_u32 v1, v11, v8, 1
	s_add_i32 s66, s25, 0
	v_readlane_b32 s4, v253, 50
	v_lshl_add_u32 v190, v9, 10, v1
	s_add_i32 m0, s66, 0x10000
	v_readlane_b32 s5, v253, 51
	v_lshl_add_u32 v178, v10, 10, v1
	s_add_i32 s67, s66, 0x2000
	s_add_i32 s80, s66, 0x4000
	s_add_i32 s81, s66, 0x6000
	s_nop 0
	global_load_lds_dwordx4 v190, s[4:5]
	s_add_i32 m0, s66, 0x12000
	s_nop 0
	global_load_lds_dwordx4 v174, s[4:5]
	v_readlane_b32 s4, v253, 44
	s_add_i32 m0, s66, 0x14000
	v_readlane_b32 s5, v253, 45
	s_nop 4
	global_load_lds_dwordx4 v190, s[4:5]
	s_add_i32 m0, s66, 0x16000
	s_nop 0
	global_load_lds_dwordx4 v174, s[4:5]
	v_readlane_b32 s4, v253, 46
	s_mov_b32 m0, s66
	v_readlane_b32 s5, v253, 47
	s_nop 4
	global_load_lds_dwordx4 v178, s[4:5]
	s_mov_b32 m0, s67
	s_nop 0
	global_load_lds_dwordx4 v176, s[4:5]
	v_readlane_b32 s4, v253, 48
	s_mov_b32 m0, s80
	v_readlane_b32 s5, v253, 49
	s_nop 4
	global_load_lds_dwordx4 v178, s[4:5]
	s_mov_b32 m0, s81
	s_nop 0
	global_load_lds_dwordx4 v176, s[4:5]
	s_ashr_i32 s4, s0, 8
	s_cmp_eq_u32 s4, 1
	s_cselect_b64 s[26:27], -1, 0
	s_cmp_lg_u32 s4, 1
	s_cbranch_scc1 .LBB0_782
	s_barrier
	s_setprio 1

; #define PG8_WAIT_V(n) asm volatile("s_waitcnt vmcnt(" #n ")" ::: "memory")
; #define PG8_BAR __builtin_amdgcn_s_barrier()
; template <class Epi, class Sched, bool ALIGN_EPI = false, bool SP2 = false>
; __device__ __forceinline__ void gemm_phase(PG8_LAS unsigned char* lds, const Gemm g, const Sched& S, const Epi& E) {
;     ...
;     PG8_WAIT_V(0);
;     if constexpr (!ALIGN_EPI) { if (wr == 0) PG8_BAR; }
;     PG8_BAR;
.LBB0_794:
	s_setprio 0
	s_waitcnt vmcnt(0)
	v_readlane_b32 s80, v249, 60
	v_readlane_b32 s81, v249, 61
	s_mov_b32 s22, s42
	s_barrier

; #define PG8_STAGE(bufoff, gbase, voff) do { _Pragma("unroll") for (int _i = 0; _i < 2; ++_i) \
;         __builtin_amdgcn_global_load_lds((const unsigned*)((const char*)(gbase) + (voff)[_i]), (PG8_LAS unsigned*)(lds + (bufoff) + ldsw + _i * 8192), 16, 0, 0); } while (0)
; #define PG8_BAR __builtin_amdgcn_s_barrier()
; template <class Epi, class Sched, bool ALIGN_EPI = false, bool SP2 = false>
; __device__ __forceinline__ void gemm_phase(PG8_LAS unsigned char* lds, const Gemm g, const Sched& S, const Epi& E) {
;     ...
;     for (int i = 0; i < 2; ++i) { int R, C; stage_rc(tid * 16 + i * 8192, R, C); const int Rb = Epi::PERM ? (64 * (R >> 5) + perm32(R & 31)) : R;
;         voffA[i] = (unsigned)(R * K + C) * 2u; voffB[i] = (unsigned)(Rb * K + C) * 2u; }
;     ...
;         PG8_STAGE(PG8_SB(0, 0), cB, voffB); PG8_STAGE(PG8_SB(0, 1), cB + hstepB, voffB); PG8_STAGE(PG8_SA(0, 0), cA, voffA); PG8_STAGE(PG8_SA(0, 1), cA + hstep, voffA);
;         if (wr == 1) PG8_BAR;
.LBB0_917:
	s_andn2_b64 vcc, exec, s[26:27]
	s_cbranch_vccnz .LBB0_1052
	v_readlane_b32 s0, v252, 59
	s_waitcnt vmcnt(0) lgkmcnt(0)
	v_mov_b32_e32 v3, v0
	v_readlane_b32 s1, v252, 60
	s_mul_i32 s82, s22, 0x14000
	s_andn2_b64 vcc, exec, s[0:1]
	v_readfirstlane_b32 s36, v3
	s_cbranch_vccnz .LBB0_998
	v_lshlrev_b32_e32 v1, 4, v3
	v_add_u32_e32 v4, 0x2000, v1
	v_ashrrev_i32_e32 v2, 31, v4
	v_lshrrev_b32_e32 v2, 22, v2
	v_add_u32_e32 v2, v4, v2
	v_ashrrev_i32_e32 v2, 10, v2
	v_mul_i32_i24_e32 v5, 0x400, v2
	v_sub_u32_e32 v4, v4, v5
	v_lshrrev_b32_e32 v5, 4, v4
	v_bitop3_b32 v5, v5, v4, 32 bitop3:0x6c
	v_ashrrev_i32_e32 v4, 31, v5
	v_lshrrev_b32_e32 v4, 26, v4
	v_add_u32_e32 v6, v5, v4
	v_lshlrev_b32_e32 v8, 3, v2
	v_ashrrev_i32_e32 v4, 6, v6
	v_and_b32_e32 v8, -16, v8
	v_add_u32_e32 v8, v4, v8
	v_lshrrev_b32_e32 v9, 2, v8
	v_lshlrev_b32_e32 v10, 1, v8
	v_and_b32_e32 v6, 0xc0, v6
	v_and_b32_e32 v7, 3, v4
	v_and_b32_e32 v9, 4, v9
	v_and_b32_e32 v10, 0xfffd8, v10
	v_sub_u32_e32 v5, v5, v6
	v_or3_b32 v7, v7, v9, v10
	v_lshlrev_b32_e32 v9, 5, v2
	v_ashrrev_i16_sdwa v5, v225, sext(v5) dst_sel:DWORD dst_unused:UNUSED_PAD src0_sel:DWORD src1_sel:BYTE_0
	v_and_b32_e32 v9, 32, v9
	v_bfe_i32 v5, v5, 0, 16
	v_add_lshl_u32 v6, v9, v5, 1
	v_lshl_add_u32 v206, v7, 12, v6
	v_lshl_add_u32 v208, v8, 12, v6
	v_bfe_i32 v6, v3, 27, 1
	v_lshrrev_b32_e32 v6, 22, v6
	v_add_u32_e32 v6, v1, v6
	v_and_b32_e32 v6, 0xfffffc00, v6
	v_sub_u32_e32 v1, v1, v6
	v_lshrrev_b32_e32 v6, 4, v1
	v_ashrrev_i32_e32 v7, 31, v3
	v_bitop3_b32 v1, v6, v1, 32 bitop3:0x6c
	v_lshrrev_b32_e32 v7, 26, v7
	v_ashrrev_i32_e32 v6, 31, v1
	v_add_u32_e32 v7, v3, v7
	v_lshrrev_b32_e32 v6, 26, v6
	v_ashrrev_i32_e32 v7, 6, v7
	v_add_u32_e32 v8, v1, v6
	v_lshlrev_b32_e32 v10, 3, v7
	v_ashrrev_i32_e32 v6, 6, v8
	v_and_b32_e32 v10, -16, v10
	v_add_u32_e32 v10, v6, v10
	v_lshrrev_b32_e32 v11, 2, v10
	v_lshlrev_b32_e32 v12, 1, v10
	v_and_b32_e32 v8, 0xc0, v8
	v_and_b32_e32 v9, 3, v6
	v_and_b32_e32 v11, 4, v11
	v_and_b32_e32 v12, 0xfffd8, v12
	v_sub_u32_e32 v1, v1, v8
	s_ashr_i32 s37, s36, 6
	v_or3_b32 v9, v9, v11, v12
	v_lshlrev_b32_e32 v11, 5, v7
	v_ashrrev_i16_sdwa v1, v225, sext(v1) dst_sel:DWORD dst_unused:UNUSED_PAD src0_sel:DWORD src1_sel:BYTE_0
	s_lshl_b32 s25, s37, 10
	v_and_b32_e32 v11, 32, v11
	v_bfe_i32 v8, v1, 0, 16
	v_add_lshl_u32 v1, v11, v8, 1
	s_add_i32 s66, s25, 0
	v_readlane_b32 s0, v254, 36
	v_lshl_add_u32 v190, v9, 12, v1
	s_add_i32 m0, s66, 0x10000
	v_readlane_b32 s1, v254, 37
	v_lshl_add_u32 v210, v10, 12, v1
	s_add_i32 s67, s66, 0x2000
	s_add_i32 s59, s66, 0x4000
	s_add_i32 s74, s66, 0x6000
	s_ashr_i32 s38, s36, 8
	global_load_lds_dwordx4 v190, s[0:1]
	s_add_i32 m0, s66, 0x12000
	s_mov_b32 s20, s22
	global_load_lds_dwordx4 v206, s[0:1]
	v_readlane_b32 s0, v254, 30
	s_add_i32 m0, s66, 0x14000
	v_readlane_b32 s1, v254, 31
	s_nop 4
	global_load_lds_dwordx4 v190, s[0:1]
	s_add_i32 m0, s66, 0x16000
	s_cmp_eq_u32 s38, 1
	global_load_lds_dwordx4 v206, s[0:1]
	v_readlane_b32 s0, v254, 32
	s_mov_b32 m0, s66
	v_readlane_b32 s1, v254, 33
	s_cselect_b64 s[26:27], -1, 0
	s_cmp_lg_u32 s38, 1
	s_nop 2
	global_load_lds_dwordx4 v210, s[0:1]
	s_mov_b32 m0, s67
	s_nop 0
	global_load_lds_dwordx4 v208, s[0:1]
	v_readlane_b32 s0, v254, 34
	s_mov_b32 m0, s59
	v_readlane_b32 s1, v254, 35
	s_nop 4
	global_load_lds_dwordx4 v210, s[0:1]
	s_mov_b32 m0, s74
	s_nop 0
	global_load_lds_dwordx4 v208, s[0:1]
	s_cbranch_scc1 .LBB0_921
	s_barrier
	s_setprio 1

; #define PG8_WAIT_V(n) asm volatile("s_waitcnt vmcnt(" #n ")" ::: "memory")
; #define PG8_BAR __builtin_amdgcn_s_barrier()
; template <class Epi, class Sched, bool ALIGN_EPI = false, bool SP2 = false>
; __device__ __forceinline__ void gemm_phase(PG8_LAS unsigned char* lds, const Gemm g, const Sched& S, const Epi& E) {
;     ...
;     PG8_WAIT_V(0);
;     if constexpr (!ALIGN_EPI) { if (wr == 0) PG8_BAR; }
;     PG8_BAR;
.LBB0_997:
	s_setprio 0
	s_waitcnt vmcnt(0)
	v_readlane_b32 s86, v249, 56
	v_readlane_b32 s96, v249, 58
	v_readlane_b32 s80, v249, 60
	s_mov_b32 s22, s20
	v_readlane_b32 s20, v252, 36
	v_readlane_b32 s87, v249, 57
	v_readlane_b32 s97, v249, 59
	v_readlane_b32 s81, v249, 61
	v_readlane_b32 s21, v252, 37
	s_barrier

; #define PG8_STAGE(bufoff, gbase, voff) do { _Pragma("unroll") for (int _i = 0; _i < 2; ++_i) \
;         __builtin_amdgcn_global_load_lds((const unsigned*)((const char*)(gbase) + (voff)[_i]), (PG8_LAS unsigned*)(lds + (bufoff) + ldsw + _i * 8192), 16, 0, 0); } while (0)
; #define PG8_BAR __builtin_amdgcn_s_barrier()
; template <class Epi, class Sched, bool ALIGN_EPI = false, bool SP2 = false>
; __device__ __forceinline__ void gemm_phase(PG8_LAS unsigned char* lds, const Gemm g, const Sched& S, const Epi& E) {
;     ...
;     for (int i = 0; i < 2; ++i) { int R, C; stage_rc(tid * 16 + i * 8192, R, C); const int Rb = Epi::PERM ? (64 * (R >> 5) + perm32(R & 31)) : R;
;         voffA[i] = (unsigned)(R * K + C) * 2u; voffB[i] = (unsigned)(Rb * K + C) * 2u; }
;     ...
;         PG8_STAGE(PG8_SB(0, 0), cB, voffB); PG8_STAGE(PG8_SB(0, 1), cB + hstepB, voffB); PG8_STAGE(PG8_SA(0, 0), cA, voffA); PG8_STAGE(PG8_SA(0, 1), cA + hstep, voffA);
;         if (wr == 1) PG8_BAR;
.LBB0_1056:
	s_add_i32 s66, s25, s59
	v_readlane_b32 s4, v250, 10
	v_readlane_b32 s5, v250, 11
	s_cmp_le_i32 s4, s66
	s_cselect_b64 s[0:1], -1, 0
	s_cmp_lt_i32 s66, s5
	s_cselect_b64 s[4:5], -1, 0
	s_and_b64 s[0:1], s[0:1], s[4:5]
	s_andn2_b64 vcc, exec, s[0:1]
	s_cbranch_vccnz .LBB0_1055
	s_cmp_eq_u32 s59, 0
	s_cbranch_scc1 .LBB0_1173
	v_readlane_b32 s0, v252, 61
	v_mov_b32_e32 v6, v0
	v_readlane_b32 s1, v252, 62
	s_andn2_b64 vcc, exec, s[0:1]
	v_readfirstlane_b32 s4, v6
	s_cbranch_vccnz .LBB0_1175
	v_lshlrev_b32_e32 v1, 4, v6
	v_add_u32_e32 v2, 0x2000, v1
	s_waitcnt vmcnt(0) lgkmcnt(0)
	v_ashrrev_i32_e32 v3, 31, v2
	v_lshrrev_b32_e32 v3, 22, v3
	v_add_u32_e32 v3, v2, v3
	v_ashrrev_i32_e32 v7, 10, v3
	v_mul_i32_i24_e32 v3, 0x400, v7
	v_sub_u32_e32 v2, v2, v3
	v_lshrrev_b32_e32 v3, 4, v2
	v_bitop3_b32 v2, v3, v2, 32 bitop3:0x6c
	v_ashrrev_i32_e32 v3, 31, v2
	v_lshrrev_b32_e32 v3, 26, v3
	v_add_u32_e32 v3, v2, v3
	v_lshlrev_b32_e32 v5, 3, v7
	v_ashrrev_i32_e32 v8, 6, v3
	v_and_b32_e32 v5, -16, v5
	v_add_u32_e32 v5, v8, v5
	v_lshrrev_b32_e32 v9, 2, v5
	v_lshlrev_b32_e32 v10, 1, v5
	v_and_b32_e32 v3, 0xc0, v3
	v_and_b32_e32 v4, 3, v8
	v_and_b32_e32 v9, 4, v9
	v_and_b32_e32 v10, 0x3ffd8, v10
	v_sub_u32_e32 v2, v2, v3
	v_or3_b32 v4, v4, v9, v10
	v_lshlrev_b32_e32 v9, 5, v7
	v_ashrrev_i16_sdwa v2, v225, sext(v2) dst_sel:DWORD dst_unused:UNUSED_PAD src0_sel:DWORD src1_sel:BYTE_0
	v_and_b32_e32 v10, 32, v9
	v_bfe_i32 v9, v2, 0, 16
	v_add_lshl_u32 v2, v10, v9, 1
	v_lshl_add_u32 v142, v4, 14, v2
	v_lshl_add_u32 v144, v5, 14, v2
	v_bfe_i32 v2, v6, 27, 1
	v_lshrrev_b32_e32 v2, 22, v2
	v_add_u32_e32 v2, v1, v2
	v_and_b32_e32 v2, 0xfffffc00, v2
	v_sub_u32_e32 v1, v1, v2
	v_lshrrev_b32_e32 v2, 4, v1
	v_ashrrev_i32_e32 v4, 31, v6
	v_bitop3_b32 v1, v2, v1, 32 bitop3:0x6c
	v_lshrrev_b32_e32 v4, 26, v4
	v_ashrrev_i32_e32 v2, 31, v1
	v_add_u32_e32 v4, v6, v4
	v_lshrrev_b32_e32 v2, 26, v2
	v_ashrrev_i32_e32 v11, 6, v4
	v_add_u32_e32 v2, v1, v2
	v_lshlrev_b32_e32 v4, 3, v11
	s_add_i32 s82, s59, -1
	v_ashrrev_i32_e32 v10, 6, v2
	v_and_b32_e32 v4, -16, v4
	s_lshl_b32 s0, s82, 27
	v_add_u32_e32 v4, v10, v4
	s_and_b32 s0, s0, 0x8000000
	v_lshrrev_b32_e32 v5, 2, v4
	v_lshlrev_b32_e32 v12, 1, v4
	v_and_b32_e32 v2, 0xc0, v2
	s_add_u32 s0, s64, s0
	v_and_b32_e32 v3, 3, v10
	v_and_b32_e32 v5, 4, v5
	v_and_b32_e32 v12, 0x3ffd8, v12
	v_sub_u32_e32 v1, v1, v2
	s_addc_u32 s1, s65, 0
	s_ashr_i32 s6, s4, 6
	v_or3_b32 v3, v3, v5, v12
	v_lshlrev_b32_e32 v5, 5, v11
	v_ashrrev_i16_sdwa v1, v225, sext(v1) dst_sel:DWORD dst_unused:UNUSED_PAD src0_sel:DWORD src1_sel:BYTE_0
	s_lshl_b32 s67, s6, 10
	v_and_b32_e32 v5, 32, v5
	v_bfe_i32 v12, v1, 0, 16
	v_add_lshl_u32 v1, v5, v12, 1
	s_add_i32 s74, s67, 0
	v_readlane_b32 s8, v249, 13
	v_lshl_add_u32 v146, v3, 14, v1
	s_add_i32 m0, s74, 0x10000
	v_readlane_b32 s9, v249, 14
	s_ashr_i32 s5, s4, 8
	v_lshl_add_u32 v190, v4, 14, v1
	v_mov_b32_e32 v145, v191
	s_nop 1
	global_load_lds_dwordx4 v146, s[8:9]
	s_add_i32 m0, s74, 0x12000
	s_nop 0
	global_load_lds_dwordx4 v142, s[8:9]
	v_readlane_b32 s8, v249, 26
	s_add_i32 m0, s74, 0x14000
	v_readlane_b32 s9, v249, 27
	s_nop 4
	global_load_lds_dwordx4 v146, s[8:9]
	s_add_i32 m0, s74, 0x16000
	s_nop 0
	global_load_lds_dwordx4 v142, s[8:9]
	v_readlane_b32 s8, v249, 24
	v_readlane_b32 s9, v249, 25
	s_add_u32 s38, s0, s8
	s_addc_u32 s39, s1, s9
	s_add_i32 s75, s74, 0x2000
	s_mov_b32 m0, s74
	s_add_u32 s8, s38, 0x200000
	global_load_lds_dwordx4 v190, s[38:39]
	s_mov_b32 m0, s75
	s_addc_u32 s9, s39, 0
	s_add_i32 s86, s74, 0x4000
	global_load_lds_dwordx4 v144, s[38:39]
	s_mov_b32 m0, s86
	s_add_i32 s87, s74, 0x6000
	global_load_lds_dwordx4 v190, s[8:9]
	s_mov_b32 m0, s87
	s_cmp_eq_u32 s5, 1
	global_load_lds_dwordx4 v144, s[8:9]
	v_lshl_add_u64 v[2:3], s[38:39], 0, v[190:191]
	s_cselect_b64 s[54:55], -1, 0
	s_cmp_lg_u32 s5, 1
	v_lshl_add_u64 v[4:5], s[38:39], 0, v[144:145]
	s_cbranch_scc1 .LBB0_1061
	s_barrier
	s_setprio 1

; #define PG8_WAIT_V(n) asm volatile("s_waitcnt vmcnt(" #n ")" ::: "memory")
; #define PG8_BAR __builtin_amdgcn_s_barrier()
; template <class Epi, class Sched, bool ALIGN_EPI = false, bool SP2 = false>
; __device__ __forceinline__ void gemm_phase(PG8_LAS unsigned char* lds, const Gemm g, const Sched& S, const Epi& E) {
;     ...
;     PG8_WAIT_V(0);
;     if constexpr (!ALIGN_EPI) { if (wr == 0) PG8_BAR; }
;     PG8_BAR;
.LBB0_1174:
	s_setprio 0
	s_waitcnt vmcnt(0)
	v_readlane_b32 s86, v249, 56
	v_readlane_b32 s96, v249, 58
	v_readlane_b32 s80, v249, 60
	v_readlane_b32 s87, v249, 57
	v_readlane_b32 s97, v249, 59
	v_readlane_b32 s81, v249, 61
	s_barrier

; #define PG8_STAGE(bufoff, gbase, voff) do { _Pragma("unroll") for (int _i = 0; _i < 2; ++_i) \
;         __builtin_amdgcn_global_load_lds((const unsigned*)((const char*)(gbase) + (voff)[_i]), (PG8_LAS unsigned*)(lds + (bufoff) + ldsw + _i * 8192), 16, 0, 0); } while (0)
; #define PG8_BAR __builtin_amdgcn_s_barrier()
; template <class Epi, class Sched, bool ALIGN_EPI = false, bool SP2 = false>
; __device__ __forceinline__ void gemm_phase(PG8_LAS unsigned char* lds, const Gemm g, const Sched& S, const Epi& E) {
;     ...
;     for (int i = 0; i < 2; ++i) { int R, C; stage_rc(tid * 16 + i * 8192, R, C); const int Rb = Epi::PERM ? (64 * (R >> 5) + perm32(R & 31)) : R;
;         voffA[i] = (unsigned)(R * K + C) * 2u; voffB[i] = (unsigned)(Rb * K + C) * 2u; }
;     ...
;         PG8_STAGE(PG8_SB(0, 0), cB, voffB); PG8_STAGE(PG8_SB(0, 1), cB + hstepB, voffB); PG8_STAGE(PG8_SA(0, 0), cA, voffA); PG8_STAGE(PG8_SA(0, 1), cA + hstep, voffA);
;         if (wr == 1) PG8_BAR;
.LBB0_1222:
	s_or_b64 exec, exec, s[26:27]
	s_waitcnt vmcnt(0)
	v_ashrrev_i32_e32 v2, 31, v26
	v_lshrrev_b32_e32 v2, 26, v2
	v_add_u32_e32 v2, v26, v2
	v_ashrrev_i32_e32 v6, 6, v2
	v_bfe_i32 v2, v26, 27, 1
	v_lshlrev_b32_e32 v1, 4, v26
	v_lshrrev_b32_e32 v2, 22, v2
	v_add_u32_e32 v2, v1, v2
	v_and_b32_e32 v2, 0xfffffc00, v2
	v_sub_u32_e32 v2, v1, v2
	v_lshrrev_b32_e32 v3, 4, v2
	v_bitop3_b32 v2, v3, v2, 32 bitop3:0x6c
	v_ashrrev_i32_e32 v4, 31, v2
	v_lshrrev_b32_e32 v4, 26, v4
	v_add_u32_e32 v4, v2, v4
	v_lshlrev_b32_e32 v3, 3, v6
	v_ashrrev_i32_e32 v7, 6, v4
	v_and_b32_e32 v4, 0xc0, v4
	v_and_b32_e32 v3, -16, v3
	v_sub_u32_e32 v2, v2, v4
	v_add_u32_e32 v3, v7, v3
	v_ashrrev_i16_sdwa v2, v225, sext(v2) dst_sel:DWORD dst_unused:UNUSED_PAD src0_sel:DWORD src1_sel:BYTE_0
	v_lshlrev_b32_e32 v5, 5, v6
	v_bfe_i32 v8, v2, 0, 16
	v_lshlrev_b32_e32 v2, 1, v3
	v_lshrrev_b32_e32 v4, 2, v3
	v_and_b32_e32 v5, 32, v5
	v_and_b32_e32 v4, 4, v4
	v_and_b32_e32 v9, 3, v7
	v_and_b32_e32 v2, 0xfffd8, v2
	v_or3_b32 v2, v9, v4, v2
	v_add_lshl_u32 v4, v5, v8, 1
	v_add_u32_e32 v1, 0x2000, v1
	v_lshl_add_u32 v130, v2, 12, v4
	v_ashrrev_i32_e32 v2, 31, v1
	v_lshrrev_b32_e32 v2, 22, v2
	v_add_u32_e32 v2, v1, v2
	v_ashrrev_i32_e32 v9, 10, v2
	v_mul_i32_i24_e32 v2, 0x400, v9
	v_sub_u32_e32 v1, v1, v2
	v_lshrrev_b32_e32 v2, 4, v1
	v_bitop3_b32 v1, v2, v1, 32 bitop3:0x6c
	v_lshl_add_u32 v190, v3, 12, v4
	v_ashrrev_i32_e32 v3, 31, v1
	v_lshrrev_b32_e32 v3, 26, v3
	v_add_u32_e32 v3, v1, v3
	s_lshl_b64 s[0:1], s[82:83], 12
	v_lshlrev_b32_e32 v2, 3, v9
	v_ashrrev_i32_e32 v10, 6, v3
	v_and_b32_e32 v3, 0xc0, v3
	s_add_u32 s0, s52, s0
	v_and_b32_e32 v2, -16, v2
	v_sub_u32_e32 v1, v1, v3
	s_addc_u32 s1, s53, s1
	s_ashr_i32 s4, s36, 6
	v_add_u32_e32 v2, v10, v2
	v_ashrrev_i16_sdwa v1, v225, sext(v1) dst_sel:DWORD dst_unused:UNUSED_PAD src0_sel:DWORD src1_sel:BYTE_0
	v_lshlrev_b32_e32 v4, 5, v9
	v_bfe_i32 v11, v1, 0, 16
	v_lshlrev_b32_e32 v1, 1, v2
	v_lshrrev_b32_e32 v3, 2, v2
	s_lshl_b32 s42, s4, 10
	v_and_b32_e32 v4, 32, v4
	v_and_b32_e32 v3, 4, v3
	v_and_b32_e32 v5, 3, v10
	v_and_b32_e32 v1, 0xfffd8, v1
	s_add_i32 s51, s42, 0
	v_readlane_b32 s6, v252, 17
	v_or3_b32 v1, v5, v3, v1
	v_add_lshl_u32 v3, v4, v11, 1
	s_add_i32 m0, s51, 0x10000
	v_readlane_b32 s7, v252, 18
	v_lshl_add_u32 v134, v1, 12, v3
	s_ashr_i32 s5, s36, 8
	v_lshl_add_u32 v132, v2, 12, v3
	v_mov_b32_e32 v133, v191
	s_nop 0
	global_load_lds_dwordx4 v130, s[6:7]
	s_add_i32 m0, s51, 0x12000
	s_nop 0
	global_load_lds_dwordx4 v134, s[6:7]
	v_readlane_b32 s6, v249, 11
	s_add_i32 m0, s51, 0x14000
	v_readlane_b32 s7, v249, 12
	s_nop 4
	global_load_lds_dwordx4 v130, s[6:7]
	s_add_i32 m0, s51, 0x16000
	s_nop 0
	global_load_lds_dwordx4 v134, s[6:7]
	v_readlane_b32 s6, v249, 31
	v_readlane_b32 s7, v249, 32
	s_add_u32 s68, s0, s6
	s_addc_u32 s69, s1, s7
	s_add_i32 s67, s51, 0x2000
	s_mov_b32 m0, s51
	s_add_u32 s6, s68, 0x80000
	global_load_lds_dwordx4 v190, s[68:69]
	s_mov_b32 m0, s67
	s_addc_u32 s7, s69, 0
	s_add_i32 s74, s51, 0x4000
	global_load_lds_dwordx4 v132, s[68:69]
	s_mov_b32 m0, s74
	s_add_i32 s75, s51, 0x6000
	global_load_lds_dwordx4 v190, s[6:7]
	s_mov_b32 m0, s75
	s_cmp_eq_u32 s5, 1
	global_load_lds_dwordx4 v132, s[6:7]
	v_lshl_add_u64 v[2:3], s[68:69], 0, v[190:191]
	s_cselect_b64 s[26:27], -1, 0
	s_cmp_lg_u32 s5, 1
	v_lshl_add_u64 v[4:5], s[68:69], 0, v[132:133]
	s_cbranch_scc1 .LBB0_1224
	s_barrier
	s_setprio 1
